# same slack delays in phases I and J, now timed with the constant-rate s_memrealtime counter (about 11 us) instead of s_sleep counts, so they do not scale with the shader clock
# baseline (speedup 1.0000x reference)
; #define PH_BEGIN if (ph >= ph_lo && ph < ph_hi) { KArgs* ap_ = (KArgs*)__builtin_amdgcn_kernarg_segment_ptr(); asm volatile("" : "+s"(ap_)); KArgs& a = *ap_; \
;         int l = lv; asm volatile("" : "+s"(l)); int G = gridDim.x, c = blockIdx.x; asm volatile("" : "+s"(G), "+s"(c)); unsigned char* ws = a.ws; (void)l; (void)G; (void)c; (void)ws;
; __global__ __launch_bounds__(512, 2) void mega(Args a_) {
;     ...
;         PH_BEGIN {
;             { pg8::StdProb P(WSP(OFF_HN), WSP(OFF_WB), DM, DM, DM, 0, 0, l == DEPTH - 1 ? 128 : 136, 16, 1, G, c); P.skipctx = l == DEPTH - 1;
;               pg8::gemm_phase<false, true>(lds, P, EpiSqReluP{WSP(OFF_R1)}); }
.LBB0_1214:
	s_andn2_b64 vcc, exec, s[0:1]
	s_cbranch_vccnz .LBB0_1323
	v_readlane_b32 s8, v237, 2
	v_readlane_b32 s9, v237, 3
	s_cmp_gt_u32 s46, 2
	s_cbranch_scc1 .Li_nodelay
	s_cmpk_lt_i32 s84, 0x80
	s_cbranch_scc1 .Li_nodelay
	s_load_dword s100, s[8:9], 0xf0
	s_waitcnt lgkmcnt(0)
	s_cmpk_lg_i32 s100, 0x100
	s_cbranch_scc1 .Li_nodelay
	s_memrealtime s[100:101]
	s_waitcnt lgkmcnt(0)
	s_add_u32 s101, s100, 1100
.Li_dly_spin:
	s_sleep 8
	s_memrealtime s[98:99]
	s_waitcnt lgkmcnt(0)
	s_sub_u32 s98, s101, s98
	s_cmp_gt_i32 s98, 0
	s_cbranch_scc1 .Li_dly_spin

; #define PH_BEGIN if (ph >= ph_lo && ph < ph_hi) { KArgs* ap_ = (KArgs*)__builtin_amdgcn_kernarg_segment_ptr(); asm volatile("" : "+s"(ap_)); KArgs& a = *ap_; \
;         int l = lv; asm volatile("" : "+s"(l)); int G = gridDim.x, c = blockIdx.x; asm volatile("" : "+s"(G), "+s"(c)); unsigned char* ws = a.ws; (void)l; (void)G; (void)c; (void)ws;
; __global__ __launch_bounds__(512, 2) void mega(Args a_) {
;     ...
;         PH_BEGIN {
;             const EpiResid E{(float*)(ws + OFF_XC), a.out, (const float*)(ws + OFF_MODS) + (size_t)l * 9 * 6144, 5, (float*)(ws + OFF_A2)};
;             if (l == DEPTH - 1) { pg8::StdProb P(WSP(OFF_R1), WSP(OFF_WB) + (size_t)HID * DM, 64, 64, HID, 0, 0, 128, 4, 1, G, c); P.skipctx = true; P.ksA = (size_t)MTOK * 128; P.ksB = (size_t)DM * 128; pg8::gemm_phase(lds, P, E); }
;             else { pg8::TailProb<4> P(WSP(OFF_R1), WSP(OFF_WB) + (size_t)HID * DM, 64, HID, G, c, G == 256); P.ksA = (size_t)MTOK * 128; P.ksB = (size_t)DM * 128; P.sliceA = (size_t)16 * MTOK * 64; P.sliceB = (size_t)16 * DM * 64;
;                    pg8::gemm_phase(lds, P, E); }
.LBB0_1326:
	v_readlane_b32 s8, v237, 2
	v_readlane_b32 s9, v237, 3
	s_cmp_gt_u32 s46, 2
	s_cbranch_scc1 .Lj_nodelay
	s_cmpk_lt_i32 s84, 0x80
	s_cbranch_scc1 .Lj_nodelay
	s_load_dword s100, s[8:9], 0xf0
	s_waitcnt lgkmcnt(0)
	s_cmpk_lg_i32 s100, 0x100
	s_cbranch_scc1 .Lj_nodelay
	s_memrealtime s[100:101]
	s_waitcnt lgkmcnt(0)
	s_add_u32 s101, s100, 1100
